# dilated chunk loop: straight-line descriptors + common path laid out as fall-through (rare blocks out of line)
# speedup vs baseline: 1.0130x; 1.0023x over previous
.LBB0_701:
	v_sub_u32_e32 v16, v16, v18
	s_and_b64 vcc, exec, s[0:1]
	s_cbranch_vccnz .Ldd_aonB
	v_cmp_gt_u32_e32 vcc, s18, v16
	v_add_u32_e32 v18, -1, v16
	s_mov_b64 s[0:1], 0
	v_cndmask_b32_e64 v112, v211, -v226, vcc
	v_cmp_gt_u32_e32 vcc, s18, v18
	v_add_u32_e32 v18, -2, v16
	s_nop 0
	v_cndmask_b32_e64 v113, v211, -v226, vcc
	v_cmp_gt_u32_e32 vcc, s18, v18
	v_add_u32_e32 v18, -3, v16
	s_nop 0
	v_cndmask_b32_e64 v114, v211, -v226, vcc
	v_cmp_gt_u32_e32 vcc, s18, v18
	v_add_u32_e32 v18, -8, v16
	s_nop 0
	v_cndmask_b32_e64 v115, v211, -v226, vcc
	v_cmp_gt_u32_e32 vcc, s18, v18
	v_add_u32_e32 v18, -9, v16
	s_nop 0
	v_cndmask_b32_e64 v116, v211, -v226, vcc
	v_cmp_gt_u32_e32 vcc, s18, v18
	v_add_u32_e32 v18, -10, v16
	s_nop 0
	v_cndmask_b32_e64 v117, v211, -v226, vcc
	v_cmp_gt_u32_e32 vcc, s18, v18
	v_add_u32_e32 v18, -11, v16
	s_nop 0
	v_cndmask_b32_e64 v118, v211, -v226, vcc
	v_cmp_gt_u32_e32 vcc, s18, v18
	v_add_u32_e32 v18, -16, v16
	s_nop 0
	v_cndmask_b32_e64 v119, v211, -v226, vcc
	v_cmp_gt_u32_e32 vcc, s18, v18
	v_subrev_u32_e32 v18, 17, v16
	s_nop 0
	v_cndmask_b32_e64 v120, v211, -v226, vcc
	v_cmp_gt_u32_e32 vcc, s18, v18
	v_subrev_u32_e32 v18, 18, v16
	s_nop 0
	v_cndmask_b32_e64 v121, v211, -v226, vcc
	v_cmp_gt_u32_e32 vcc, s18, v18
	v_subrev_u32_e32 v18, 19, v16
	s_nop 0
	v_cndmask_b32_e64 v122, v211, -v226, vcc
	v_cmp_gt_u32_e32 vcc, s18, v18
	v_subrev_u32_e32 v18, 24, v16
	s_nop 0
	v_cndmask_b32_e64 v123, v211, -v226, vcc
	v_cmp_gt_u32_e32 vcc, s18, v18
	v_subrev_u32_e32 v18, 25, v16
	s_nop 0
	v_cndmask_b32_e64 v124, v211, -v226, vcc
	v_cmp_gt_u32_e32 vcc, s18, v18
	v_subrev_u32_e32 v18, 26, v16
	s_nop 0
	v_cndmask_b32_e64 v125, v211, -v226, vcc
	v_cmp_gt_u32_e32 vcc, s18, v18
	v_subrev_u32_e32 v18, 27, v16
	s_nop 0
	v_cndmask_b32_e64 v126, v211, -v226, vcc
	v_cmp_gt_u32_e32 vcc, s18, v18
	s_nop 1
	v_cndmask_b32_e64 v127, v211, -v226, vcc
.LBB0_705:
	s_waitcnt lgkmcnt(0)
	ds_read_b128 v[192:195], v217
	ds_read_b128 v[26:29], v217 offset:32
	ds_read_b128 v[22:25], v217 offset:64
	ds_read_b128 v[18:21], v217 offset:96
	s_andn2_b64 s[0:1], exec, s[2:3]
	s_and_b64 vcc, exec, s[2:3]
	s_cbranch_vccz .Ldd_noqa
	s_waitcnt lgkmcnt(3)
	v_mfma_f32_32x32x16_bf16 v[0:15], v[192:195], v[128:131], v[0:15]
	s_waitcnt lgkmcnt(2)
	v_mfma_f32_32x32x16_bf16 v[0:15], v[26:29], v[132:135], v[0:15]
	s_waitcnt lgkmcnt(1)
	v_mfma_f32_32x32x16_bf16 v[0:15], v[22:25], v[136:139], v[0:15]
	s_waitcnt lgkmcnt(0)
	v_mfma_f32_32x32x16_bf16 v[0:15], v[18:21], v[140:143], v[0:15]
.Ldd_noqa:
	s_andn2_b64 s[2:3], exec, s[14:15]
	s_and_b64 vcc, exec, s[14:15]
	s_cbranch_vccz .Ldd_noqb
	s_waitcnt lgkmcnt(3)
	v_mfma_f32_32x32x16_bf16 v[112:127], v[192:195], v[152:155], v[112:127]
	s_waitcnt lgkmcnt(2)
	v_mfma_f32_32x32x16_bf16 v[112:127], v[26:29], v[144:147], v[112:127]
	s_waitcnt lgkmcnt(1)
	v_mfma_f32_32x32x16_bf16 v[112:127], v[22:25], v[148:151], v[112:127]
	s_waitcnt lgkmcnt(0)
	v_mfma_f32_32x32x16_bf16 v[112:127], v[18:21], v[156:159], v[112:127]

.LBB0_708:
	s_nop 7
	v_max_f32_e32 v16, v1, v1
	s_waitcnt lgkmcnt(0)
	v_max_f32_e32 v18, v0, v0
	v_max_f32_e32 v16, v18, v16
	v_max3_f32 v16, v16, v2, v3
	v_max3_f32 v16, v16, v4, v5
	v_max3_f32 v16, v16, v6, v7
	v_max3_f32 v16, v16, v8, v9
	v_max3_f32 v16, v16, v10, v11
	v_max3_f32 v16, v16, v12, v13
	v_max3_f32 v16, v16, v14, v15
	v_mov_b32_e32 v18, v16
	s_nop 1
	v_permlane32_swap_b32_e32 v16, v18
	v_max_f32_e32 v18, v18, v18
	v_max_f32_e32 v16, v16, v16
	v_max_f32_e32 v16, v16, v18
	v_cmp_lt_f32_e32 vcc, s28, v16
	s_cbranch_vccnz .Ldd_rescA

.LBB0_714:
	ds_read_b64_tr_b16 v[12:13], v218 offset:4608
	ds_read_b64_tr_b16 v[14:15], v218 offset:5120
	ds_read_b64_tr_b16 v[4:5], v218 offset:5632
	ds_read_b64_tr_b16 v[6:7], v218 offset:6144
	ds_read_b64_tr_b16 v[8:9], v218 offset:6656
	ds_read_b64_tr_b16 v[10:11], v218 offset:7168
	ds_read_b64_tr_b16 v[0:1], v218 offset:7680
	ds_read_b64_tr_b16 v[2:3], v218 offset:8192
	s_waitcnt lgkmcnt(0)
	s_and_b64 vcc, exec, s[0:1]
	s_cbranch_vccnz .Ldd_nopva
	s_waitcnt lgkmcnt(6)
	v_mfma_f32_32x32x16_bf16 v[96:111], v[12:15], v[22:25], v[96:111]
	s_waitcnt lgkmcnt(2)
	v_mfma_f32_32x32x16_bf16 v[48:63], v[8:11], v[22:25], v[48:63]
	v_mfma_f32_32x32x16_bf16 v[96:111], v[4:7], v[18:21], v[96:111]
	s_waitcnt lgkmcnt(0)
	v_mfma_f32_32x32x16_bf16 v[48:63], v[0:3], v[18:21], v[48:63]

.LBB0_718:
	v_max_f32_e32 v16, v113, v113
	v_max_f32_e32 v18, v112, v112
	v_max_f32_e32 v16, v18, v16
	v_max3_f32 v16, v16, v114, v115
	v_max3_f32 v16, v16, v116, v117
	v_max3_f32 v16, v16, v118, v119
	v_max3_f32 v16, v16, v120, v121
	v_max3_f32 v16, v16, v122, v123
	v_max3_f32 v16, v16, v124, v125
	v_max3_f32 v16, v16, v126, v127
	v_mov_b32_e32 v18, v16
	s_nop 1
	v_permlane32_swap_b32_e32 v16, v18
	s_cmp_eq_u32 s68, 0
	v_max_f32_e32 v18, v18, v18
	v_max_f32_e32 v16, v16, v16
	s_cselect_b64 s[0:1], -1, 0
	v_max_f32_e32 v16, v16, v18
	s_cbranch_scc1 .Ldd_rescB
	v_cmp_lt_f32_e32 vcc, s28, v16
	s_cbranch_vccnz .Ldd_rescB

.LBB0_725:
	s_mov_b32 s70, s69
	s_branch .LBB0_663
.Ldd_f16:
	s_sub_i32 s0, s45, s69
	s_lshl_b32 s0, s0, 5
	s_add_i32 s1, s67, s68
	s_cmp_gt_u32 s69, s46
	s_cselect_b32 s2, s1, s0
	s_cselect_b32 s14, s23, s19
	s_mov_b32 s3, 16
	s_branch .LBB0_676

.Ldd_aonA:
	v_cmp_lt_i32_e32 vcc, 0, v19
	s_nop 1
	v_cndmask_b32_e64 v0, v211, -v209, vcc
	v_mov_b32_e32 v1, v0
	s_waitcnt lgkmcnt(8)
	v_mov_b32_e32 v2, v0
	v_mov_b32_e32 v3, v0
	v_mov_b32_e32 v4, v0
	v_mov_b32_e32 v5, v0
	v_mov_b32_e32 v6, v0
	v_mov_b32_e32 v7, v0
	v_mov_b32_e32 v8, v0
	v_mov_b32_e32 v9, v0
	v_mov_b32_e32 v10, v0
	v_mov_b32_e32 v11, v0
	v_mov_b32_e32 v12, v0
	v_mov_b32_e32 v13, v0
	v_mov_b32_e32 v14, v0
	v_mov_b32_e32 v15, v0
	s_branch .LBB0_701
.Ldd_aonB:
	v_cmp_lt_i32_e32 vcc, 0, v16
	s_nop 1
	v_cndmask_b32_e64 v112, v211, -v226, vcc
	v_mov_b32_e32 v113, v112
	v_mov_b32_e32 v114, v112
	v_mov_b32_e32 v115, v112
	v_mov_b32_e32 v116, v112
	v_mov_b32_e32 v117, v112
	v_mov_b32_e32 v118, v112
	v_mov_b32_e32 v119, v112
	v_mov_b32_e32 v120, v112
	v_mov_b32_e32 v121, v112
	v_mov_b32_e32 v122, v112
	v_mov_b32_e32 v123, v112
	v_mov_b32_e32 v124, v112
	v_mov_b32_e32 v125, v112
	v_mov_b32_e32 v126, v112
	v_mov_b32_e32 v127, v112
	s_branch .LBB0_705
.Ldd_rescA:
	v_max_f32_e32 v16, v16, v16
	v_max_f32_e32 v16, 0, v16
	v_exp_f32_e64 v18, -v16
	v_add_f32_e32 v209, v209, v16
	v_pk_add_f32 v[0:1], v[0:1], v[16:17] op_sel_hi:[1,0] neg_lo:[0,1] neg_hi:[0,1]
	v_pk_add_f32 v[2:3], v[2:3], v[16:17] op_sel_hi:[1,0] neg_lo:[0,1] neg_hi:[0,1]
	v_pk_add_f32 v[4:5], v[4:5], v[16:17] op_sel_hi:[1,0] neg_lo:[0,1] neg_hi:[0,1]
	v_pk_add_f32 v[6:7], v[6:7], v[16:17] op_sel_hi:[1,0] neg_lo:[0,1] neg_hi:[0,1]
	v_pk_add_f32 v[8:9], v[8:9], v[16:17] op_sel_hi:[1,0] neg_lo:[0,1] neg_hi:[0,1]
	v_pk_add_f32 v[10:11], v[10:11], v[16:17] op_sel_hi:[1,0] neg_lo:[0,1] neg_hi:[0,1]
	v_pk_add_f32 v[12:13], v[12:13], v[16:17] op_sel_hi:[1,0] neg_lo:[0,1] neg_hi:[0,1]
	v_pk_add_f32 v[14:15], v[14:15], v[16:17] op_sel_hi:[1,0] neg_lo:[0,1] neg_hi:[0,1]
	v_mul_f32_e32 v208, v208, v18
	v_pk_mul_f32 v[110:111], v[110:111], v[18:19] op_sel_hi:[1,0]
	v_pk_mul_f32 v[108:109], v[108:109], v[18:19] op_sel_hi:[1,0]
	v_pk_mul_f32 v[106:107], v[106:107], v[18:19] op_sel_hi:[1,0]
	v_pk_mul_f32 v[104:105], v[104:105], v[18:19] op_sel_hi:[1,0]
	v_pk_mul_f32 v[102:103], v[102:103], v[18:19] op_sel_hi:[1,0]
	v_pk_mul_f32 v[100:101], v[100:101], v[18:19] op_sel_hi:[1,0]
	v_pk_mul_f32 v[98:99], v[98:99], v[18:19] op_sel_hi:[1,0]
	v_pk_mul_f32 v[96:97], v[96:97], v[18:19] op_sel_hi:[1,0]
	v_pk_mul_f32 v[62:63], v[62:63], v[18:19] op_sel_hi:[1,0]
	v_pk_mul_f32 v[60:61], v[60:61], v[18:19] op_sel_hi:[1,0]
	v_pk_mul_f32 v[58:59], v[58:59], v[18:19] op_sel_hi:[1,0]
	v_pk_mul_f32 v[56:57], v[56:57], v[18:19] op_sel_hi:[1,0]
	v_pk_mul_f32 v[54:55], v[54:55], v[18:19] op_sel_hi:[1,0]
	v_pk_mul_f32 v[52:53], v[52:53], v[18:19] op_sel_hi:[1,0]
	v_pk_mul_f32 v[50:51], v[50:51], v[18:19] op_sel_hi:[1,0]
	v_pk_mul_f32 v[48:49], v[48:49], v[18:19] op_sel_hi:[1,0]
	s_branch .LBB0_710
.LBB0_713:
	s_waitcnt lgkmcnt(0)
	v_mov_b32_e32 v21, 0
	v_mov_b32_e32 v20, 0
	v_mov_b32_e32 v19, 0
	v_mov_b32_e32 v18, 0
	v_mov_b32_e32 v25, 0
	v_mov_b32_e32 v24, 0
	v_mov_b32_e32 v23, 0
	v_mov_b32_e32 v22, 0
	s_branch .LBB0_714

.Ldd_rescB:
	v_max_f32_e32 v18, v16, v16
	v_max_f32_e32 v18, 0, v18
	v_cndmask_b32_e64 v16, v18, v16, s[0:1]
	v_exp_f32_e64 v18, -v16
	v_add_f32_e32 v226, v226, v16
	v_pk_add_f32 v[112:113], v[112:113], v[16:17] op_sel_hi:[1,0] neg_lo:[0,1] neg_hi:[0,1]
	v_pk_add_f32 v[114:115], v[114:115], v[16:17] op_sel_hi:[1,0] neg_lo:[0,1] neg_hi:[0,1]
	v_pk_add_f32 v[116:117], v[116:117], v[16:17] op_sel_hi:[1,0] neg_lo:[0,1] neg_hi:[0,1]
	v_pk_add_f32 v[118:119], v[118:119], v[16:17] op_sel_hi:[1,0] neg_lo:[0,1] neg_hi:[0,1]
	v_pk_add_f32 v[120:121], v[120:121], v[16:17] op_sel_hi:[1,0] neg_lo:[0,1] neg_hi:[0,1]
	v_pk_add_f32 v[122:123], v[122:123], v[16:17] op_sel_hi:[1,0] neg_lo:[0,1] neg_hi:[0,1]
	v_pk_add_f32 v[124:125], v[124:125], v[16:17] op_sel_hi:[1,0] neg_lo:[0,1] neg_hi:[0,1]
	v_pk_add_f32 v[126:127], v[126:127], v[16:17] op_sel_hi:[1,0] neg_lo:[0,1] neg_hi:[0,1]
	v_mul_f32_e32 v219, v219, v18
	v_pk_mul_f32 v[94:95], v[94:95], v[18:19] op_sel_hi:[1,0]
	v_pk_mul_f32 v[92:93], v[92:93], v[18:19] op_sel_hi:[1,0]
	v_pk_mul_f32 v[90:91], v[90:91], v[18:19] op_sel_hi:[1,0]
	v_pk_mul_f32 v[88:89], v[88:89], v[18:19] op_sel_hi:[1,0]
	v_pk_mul_f32 v[86:87], v[86:87], v[18:19] op_sel_hi:[1,0]
	v_pk_mul_f32 v[84:85], v[84:85], v[18:19] op_sel_hi:[1,0]
	v_pk_mul_f32 v[82:83], v[82:83], v[18:19] op_sel_hi:[1,0]
	v_pk_mul_f32 v[80:81], v[80:81], v[18:19] op_sel_hi:[1,0]
	v_pk_mul_f32 v[78:79], v[78:79], v[18:19] op_sel_hi:[1,0]
	v_pk_mul_f32 v[76:77], v[76:77], v[18:19] op_sel_hi:[1,0]
	v_pk_mul_f32 v[74:75], v[74:75], v[18:19] op_sel_hi:[1,0]
	v_pk_mul_f32 v[72:73], v[72:73], v[18:19] op_sel_hi:[1,0]
	v_pk_mul_f32 v[70:71], v[70:71], v[18:19] op_sel_hi:[1,0]
	v_pk_mul_f32 v[68:69], v[68:69], v[18:19] op_sel_hi:[1,0]
	v_pk_mul_f32 v[66:67], v[66:67], v[18:19] op_sel_hi:[1,0]
	v_pk_mul_f32 v[64:65], v[64:65], v[18:19] op_sel_hi:[1,0]
	s_branch .LBB0_724
